# w_in epilogue: the four per-block ss loads issued in the first row block (no store drain at later blocks), same as FFN-up
# speedup vs baseline: 1.0501x; 1.0050x over previous
; __device__ __forceinline__ u16 bf16_1(float a) { return (u16)(pk_bf16(a, 0.f) & 0xffffu); }
; __device__ void run_phase(CP& p, int ph, char* lds) {
;     ...
;         for (int tb = 0; tb < 2; ++tb) {
;           const int tok = tbase + tb * 32 + l32;
;           if (tok < M) {
;             const float rs = rsqrtf(p.ss1[tok] * (1.f / 1024.f) + EPSN);
;             if (!G.meta && nbase >= 2048 && nbase < 3072) {
;               const int s = tok >> G.lgS, t = 16 + (tok & (G.S - 1));
;               const int Lp = (G.L + 63) & ~63;
;               const int pos = (t & ~12) | ((t & 4) << 1) | ((t & 8) >> 1);
;               u16* vt = p.VT + ((size_t)(s * 1024 + (nbase - 2048)) * Lp) + pos;
; #pragma unroll
;               for (int nb = 0; nb < 2; ++nb)
; #pragma unroll
;                 for (int r = 0; r < 16; ++r) {
;                   const int dvl = nb * 32 + 8 * (r >> 2) + 4 * h + (r & 3);
;                   vt[(size_t)dvl * Lp] = bf16_1(acc[nb][tb][r] * rs);
;                 }
;             } else {
;               u16* dst = Pout + (size_t)tok * NIN + nbase + 4 * h;
; #pragma unroll
;               for (int nb = 0; nb < 2; ++nb)
; #pragma unroll
;                 for (int i = 0; i < 4; ++i)
;                   *(u32x2*)(dst + nb * 32 + 8 * i) = (u32x2){pk_bf16(acc[nb][tb][4 * i] * rs, acc[nb][tb][4 * i + 1] * rs),
;                                                              pk_bf16(acc[nb][tb][4 * i + 2] * rs, acc[nb][tb][4 * i + 3] * rs)};
;             }
.LBB0_623:
	s_or_b64 exec, exec, s[6:7]
	v_mov_b32_e32 v147, v204
	v_lshl_add_u32 v154, v170, 8, v169
	v_lshl_or_b32 v144, v160, 7, v168
	v_and_or_b32 v146, v147, 31, v154
	v_and_b32_e32 v145, 0x1fffff8, v160
	v_lshrrev_b32_e32 v147, 3, v147
	v_cmp_eq_u32_e64 s[40:41], 16, v145
	v_ashrrev_i32_e32 v145, 31, v144
	v_and_b32_e32 v155, 4, v147
	v_add_u32_e32 v153, 0xfffff800, v144
	v_cmp_gt_i32_e64 s[42:43], s62, v146
	v_ashrrev_i32_e32 v147, 31, v146
	s_and_saveexec_b64 s[34:35], s[42:43]
	s_cbranch_execz .LBB0_628
	v_lshl_add_u64 v[150:151], v[146:147], 2, s[48:49]
	global_load_dword v243, v[150:151], off offset:128
	global_load_dword v244, v[150:151], off offset:512
	global_load_dword v245, v[150:151], off offset:640
	global_load_dword v148, v[150:151], off
	s_and_b64 s[0:1], s[86:87], s[40:41]
	s_xor_b64 s[0:1], s[0:1], -1
	s_waitcnt vmcnt(0)
	v_fmamk_f32 v148, v148, 0x3a800000, v205
	v_mul_f32_e32 v150, 0x4b800000, v148
	v_cmp_gt_f32_e64 s[42:43], s21, v148
	s_nop 1
	v_cndmask_b32_e64 v148, v148, v150, s[42:43]
	v_rsq_f32_e32 v148, v148
	s_nop 0
	v_mul_f32_e32 v150, 0x45800000, v148
	v_cndmask_b32_e64 v148, v148, v150, s[42:43]
	s_and_saveexec_b64 s[6:7], s[0:1]
	s_xor_b64 s[6:7], exec, s[6:7]
	s_cbranch_execz .LBB0_626
	v_mov_b64_e32 v[150:151], s[46:47]
	v_mad_i64_i32 v[150:151], s[0:1], v146, s74, v[150:151]
	v_lshl_add_u64 v[150:151], v[144:145], 1, v[150:151]
	v_lshlrev_b32_e32 v160, 1, v155
	v_lshl_add_u64 v[150:151], v[150:151], 0, v[160:161]
	v_lshl_add_u64 v[150:151], v[150:151], 0, v[160:161]
	v_pk_mul_f32 v[112:113], v[112:113], v[148:149] op_sel_hi:[1,0]
	v_pk_mul_f32 v[114:115], v[114:115], v[148:149] op_sel_hi:[1,0]
	v_pk_mul_f32 v[116:117], v[116:117], v[148:149] op_sel_hi:[1,0]
	v_pk_mul_f32 v[118:119], v[118:119], v[148:149] op_sel_hi:[1,0]
	v_cvt_pk_bf16_f32 v222, v112, v113
	v_cvt_pk_bf16_f32 v223, v114, v115
	v_cvt_pk_bf16_f32 v224, v116, v117
	v_cvt_pk_bf16_f32 v225, v118, v119
	s_nop 1
	v_permlane32_swap_b32_e32 v222, v224
	v_permlane32_swap_b32_e32 v223, v225
	global_store_dwordx4 v[150:151], v[222:225], off
	v_pk_mul_f32 v[120:121], v[120:121], v[148:149] op_sel_hi:[1,0]
	v_pk_mul_f32 v[122:123], v[122:123], v[148:149] op_sel_hi:[1,0]
	v_pk_mul_f32 v[124:125], v[124:125], v[148:149] op_sel_hi:[1,0]
	v_pk_mul_f32 v[126:127], v[126:127], v[148:149] op_sel_hi:[1,0]
	v_cvt_pk_bf16_f32 v226, v120, v121
	v_cvt_pk_bf16_f32 v227, v122, v123
	v_cvt_pk_bf16_f32 v228, v124, v125
	v_cvt_pk_bf16_f32 v229, v126, v127
	s_nop 1
	v_permlane32_swap_b32_e32 v226, v228
	v_permlane32_swap_b32_e32 v227, v229
	global_store_dwordx4 v[150:151], v[226:229], off offset:32
	v_pk_mul_f32 v[96:97], v[96:97], v[148:149] op_sel_hi:[1,0]
	v_pk_mul_f32 v[98:99], v[98:99], v[148:149] op_sel_hi:[1,0]
	v_pk_mul_f32 v[100:101], v[100:101], v[148:149] op_sel_hi:[1,0]
	v_pk_mul_f32 v[102:103], v[102:103], v[148:149] op_sel_hi:[1,0]
	v_cvt_pk_bf16_f32 v230, v96, v97
	v_cvt_pk_bf16_f32 v231, v98, v99
	v_cvt_pk_bf16_f32 v232, v100, v101
	v_cvt_pk_bf16_f32 v233, v102, v103
	s_nop 1
	v_permlane32_swap_b32_e32 v230, v232
	v_permlane32_swap_b32_e32 v231, v233
	global_store_dwordx4 v[150:151], v[230:233], off offset:64
	v_pk_mul_f32 v[104:105], v[104:105], v[148:149] op_sel_hi:[1,0]
	v_pk_mul_f32 v[106:107], v[106:107], v[148:149] op_sel_hi:[1,0]
	v_pk_mul_f32 v[108:109], v[108:109], v[148:149] op_sel_hi:[1,0]
	v_pk_mul_f32 v[110:111], v[110:111], v[148:149] op_sel_hi:[1,0]
	v_cvt_pk_bf16_f32 v234, v104, v105
	v_cvt_pk_bf16_f32 v235, v106, v107
	v_cvt_pk_bf16_f32 v236, v108, v109
	v_cvt_pk_bf16_f32 v237, v110, v111
	s_nop 1
	v_permlane32_swap_b32_e32 v234, v236
	v_permlane32_swap_b32_e32 v235, v237
	global_store_dwordx4 v[150:151], v[234:237], off offset:96

; __device__ __forceinline__ u16 bf16_1(float a) { return (u16)(pk_bf16(a, 0.f) & 0xffffu); }
; __device__ void run_phase(CP& p, int ph, char* lds) {
;     ...
;         for (int tb = 0; tb < 2; ++tb) {
;           const int tok = tbase + tb * 32 + l32;
;           if (tok < M) {
;             const float rs = rsqrtf(p.ss1[tok] * (1.f / 1024.f) + EPSN);
;             if (!G.meta && nbase >= 2048 && nbase < 3072) {
;               const int s = tok >> G.lgS, t = 16 + (tok & (G.S - 1));
;               const int Lp = (G.L + 63) & ~63;
;               const int pos = (t & ~12) | ((t & 4) << 1) | ((t & 8) >> 1);
;               u16* vt = p.VT + ((size_t)(s * 1024 + (nbase - 2048)) * Lp) + pos;
; #pragma unroll
;               for (int nb = 0; nb < 2; ++nb)
; #pragma unroll
;                 for (int r = 0; r < 16; ++r) {
;                   const int dvl = nb * 32 + 8 * (r >> 2) + 4 * h + (r & 3);
;                   vt[(size_t)dvl * Lp] = bf16_1(acc[nb][tb][r] * rs);
;                 }
;             } else {
;               u16* dst = Pout + (size_t)tok * NIN + nbase + 4 * h;
; #pragma unroll
;               for (int nb = 0; nb < 2; ++nb)
; #pragma unroll
;                 for (int i = 0; i < 4; ++i)
;                   *(u32x2*)(dst + nb * 32 + 8 * i) = (u32x2){pk_bf16(acc[nb][tb][4 * i] * rs, acc[nb][tb][4 * i + 1] * rs),
;                                                              pk_bf16(acc[nb][tb][4 * i + 2] * rs, acc[nb][tb][4 * i + 3] * rs)};
;             }
.LBB0_628:
	s_or_b64 exec, exec, s[34:35]
	v_or_b32_e32 v97, 32, v146
	v_cmp_gt_i32_e64 s[42:43], s62, v97
	s_and_saveexec_b64 s[34:35], s[42:43]
	s_cbranch_execz .LBB0_633
	v_lshl_add_u64 v[98:99], v[146:147], 2, s[48:49]
	s_and_b64 s[0:1], s[86:87], s[40:41]
	s_xor_b64 s[0:1], s[0:1], -1
	v_mov_b32_e32 v96, v243
	v_fmamk_f32 v96, v96, 0x3a800000, v205
	v_mul_f32_e32 v98, 0x4b800000, v96
	v_cmp_gt_f32_e64 s[42:43], s21, v96
	s_nop 1
	v_cndmask_b32_e64 v96, v96, v98, s[42:43]
	v_rsq_f32_e32 v96, v96
	s_nop 0
	v_mul_f32_e32 v98, 0x45800000, v96
	v_cndmask_b32_e64 v96, v96, v98, s[42:43]
	s_and_saveexec_b64 s[6:7], s[0:1]
	s_xor_b64 s[6:7], exec, s[6:7]
	s_cbranch_execz .LBB0_631
	v_mov_b64_e32 v[98:99], s[46:47]
	v_mad_i64_i32 v[98:99], s[0:1], v97, s74, v[98:99]
	v_lshl_add_u64 v[98:99], v[144:145], 1, v[98:99]
	v_lshlrev_b32_e32 v160, 1, v155
	v_lshl_add_u64 v[98:99], v[98:99], 0, v[160:161]
	v_lshl_add_u64 v[98:99], v[98:99], 0, v[160:161]
	v_pk_mul_f32 v[80:81], v[80:81], v[96:97] op_sel_hi:[1,0]
	v_pk_mul_f32 v[82:83], v[82:83], v[96:97] op_sel_hi:[1,0]
	v_pk_mul_f32 v[84:85], v[84:85], v[96:97] op_sel_hi:[1,0]
	v_pk_mul_f32 v[86:87], v[86:87], v[96:97] op_sel_hi:[1,0]
	v_cvt_pk_bf16_f32 v222, v80, v81
	v_cvt_pk_bf16_f32 v223, v82, v83
	v_cvt_pk_bf16_f32 v224, v84, v85
	v_cvt_pk_bf16_f32 v225, v86, v87
	s_nop 1
	v_permlane32_swap_b32_e32 v222, v224
	v_permlane32_swap_b32_e32 v223, v225
	global_store_dwordx4 v[98:99], v[222:225], off
	v_pk_mul_f32 v[88:89], v[88:89], v[96:97] op_sel_hi:[1,0]
	v_pk_mul_f32 v[90:91], v[90:91], v[96:97] op_sel_hi:[1,0]
	v_pk_mul_f32 v[92:93], v[92:93], v[96:97] op_sel_hi:[1,0]
	v_pk_mul_f32 v[94:95], v[94:95], v[96:97] op_sel_hi:[1,0]
	v_cvt_pk_bf16_f32 v226, v88, v89
	v_cvt_pk_bf16_f32 v227, v90, v91
	v_cvt_pk_bf16_f32 v228, v92, v93
	v_cvt_pk_bf16_f32 v229, v94, v95
	s_nop 1
	v_permlane32_swap_b32_e32 v226, v228
	v_permlane32_swap_b32_e32 v227, v229
	global_store_dwordx4 v[98:99], v[226:229], off offset:32
	v_pk_mul_f32 v[64:65], v[64:65], v[96:97] op_sel_hi:[1,0]
	v_pk_mul_f32 v[66:67], v[66:67], v[96:97] op_sel_hi:[1,0]
	v_pk_mul_f32 v[68:69], v[68:69], v[96:97] op_sel_hi:[1,0]
	v_pk_mul_f32 v[70:71], v[70:71], v[96:97] op_sel_hi:[1,0]
	v_cvt_pk_bf16_f32 v230, v64, v65
	v_cvt_pk_bf16_f32 v231, v66, v67
	v_cvt_pk_bf16_f32 v232, v68, v69
	v_cvt_pk_bf16_f32 v233, v70, v71
	s_nop 1
	v_permlane32_swap_b32_e32 v230, v232
	v_permlane32_swap_b32_e32 v231, v233
	global_store_dwordx4 v[98:99], v[230:233], off offset:64
	v_pk_mul_f32 v[72:73], v[72:73], v[96:97] op_sel_hi:[1,0]
	v_pk_mul_f32 v[74:75], v[74:75], v[96:97] op_sel_hi:[1,0]
	v_pk_mul_f32 v[76:77], v[76:77], v[96:97] op_sel_hi:[1,0]
	v_pk_mul_f32 v[78:79], v[78:79], v[96:97] op_sel_hi:[1,0]
	v_cvt_pk_bf16_f32 v234, v72, v73
	v_cvt_pk_bf16_f32 v235, v74, v75
	v_cvt_pk_bf16_f32 v236, v76, v77
	v_cvt_pk_bf16_f32 v237, v78, v79
	s_nop 1
	v_permlane32_swap_b32_e32 v234, v236
	v_permlane32_swap_b32_e32 v235, v237
	global_store_dwordx4 v[98:99], v[234:237], off offset:96

; __device__ __forceinline__ u16 bf16_1(float a) { return (u16)(pk_bf16(a, 0.f) & 0xffffu); }
; __device__ void run_phase(CP& p, int ph, char* lds) {
;     ...
;         for (int tb = 0; tb < 2; ++tb) {
;           const int tok = tbase + tb * 32 + l32;
;           if (tok < M) {
;             const float rs = rsqrtf(p.ss1[tok] * (1.f / 1024.f) + EPSN);
;             if (!G.meta && nbase >= 2048 && nbase < 3072) {
;               const int s = tok >> G.lgS, t = 16 + (tok & (G.S - 1));
;               const int Lp = (G.L + 63) & ~63;
;               const int pos = (t & ~12) | ((t & 4) << 1) | ((t & 8) >> 1);
;               u16* vt = p.VT + ((size_t)(s * 1024 + (nbase - 2048)) * Lp) + pos;
; #pragma unroll
;               for (int nb = 0; nb < 2; ++nb)
; #pragma unroll
;                 for (int r = 0; r < 16; ++r) {
;                   const int dvl = nb * 32 + 8 * (r >> 2) + 4 * h + (r & 3);
;                   vt[(size_t)dvl * Lp] = bf16_1(acc[nb][tb][r] * rs);
;                 }
;             } else {
;               u16* dst = Pout + (size_t)tok * NIN + nbase + 4 * h;
; #pragma unroll
;               for (int nb = 0; nb < 2; ++nb)
; #pragma unroll
;                 for (int i = 0; i < 4; ++i)
;                   *(u32x2*)(dst + nb * 32 + 8 * i) = (u32x2){pk_bf16(acc[nb][tb][4 * i] * rs, acc[nb][tb][4 * i + 1] * rs),
;                                                              pk_bf16(acc[nb][tb][4 * i + 2] * rs, acc[nb][tb][4 * i + 3] * rs)};
;             }
.LBB0_633:
	s_or_b64 exec, exec, s[34:35]
	v_mov_b32_e32 v65, v204
	s_movk_i32 s0, 0x80
	v_and_b32_e32 v64, 31, v65
	v_add3_u32 v64, v154, v64, s0
	v_lshrrev_b32_e32 v65, 3, v65
	v_and_b32_e32 v67, 4, v65
	v_cmp_gt_i32_e64 s[42:43], s62, v64
	v_ashrrev_i32_e32 v65, 31, v64
	s_and_saveexec_b64 s[34:35], s[42:43]
	s_cbranch_execz .LBB0_638
	v_lshl_add_u64 v[68:69], v[64:65], 2, s[48:49]
	s_and_b64 s[0:1], s[86:87], s[40:41]
	s_xor_b64 s[0:1], s[0:1], -1
	v_mov_b32_e32 v66, v244
	v_fmamk_f32 v66, v66, 0x3a800000, v205
	v_mul_f32_e32 v68, 0x4b800000, v66
	v_cmp_gt_f32_e64 s[42:43], s21, v66
	s_nop 1
	v_cndmask_b32_e64 v66, v66, v68, s[42:43]
	v_rsq_f32_e32 v66, v66
	s_nop 0
	v_mul_f32_e32 v68, 0x45800000, v66
	v_cndmask_b32_e64 v66, v66, v68, s[42:43]
	s_and_saveexec_b64 s[6:7], s[0:1]
	s_xor_b64 s[6:7], exec, s[6:7]
	s_cbranch_execz .LBB0_636
	v_mov_b64_e32 v[68:69], s[46:47]
	v_mad_i64_i32 v[68:69], s[0:1], v64, s74, v[68:69]
	v_lshl_add_u64 v[68:69], v[144:145], 1, v[68:69]
	v_lshlrev_b32_e32 v160, 1, v67
	v_lshl_add_u64 v[68:69], v[68:69], 0, v[160:161]
	v_lshl_add_u64 v[68:69], v[68:69], 0, v[160:161]
	v_pk_mul_f32 v[48:49], v[48:49], v[66:67] op_sel_hi:[1,0]
	v_pk_mul_f32 v[50:51], v[50:51], v[66:67] op_sel_hi:[1,0]
	v_pk_mul_f32 v[52:53], v[52:53], v[66:67] op_sel_hi:[1,0]
	v_pk_mul_f32 v[54:55], v[54:55], v[66:67] op_sel_hi:[1,0]
	v_cvt_pk_bf16_f32 v222, v48, v49
	v_cvt_pk_bf16_f32 v223, v50, v51
	v_cvt_pk_bf16_f32 v224, v52, v53
	v_cvt_pk_bf16_f32 v225, v54, v55
	s_nop 1
	v_permlane32_swap_b32_e32 v222, v224
	v_permlane32_swap_b32_e32 v223, v225
	global_store_dwordx4 v[68:69], v[222:225], off
	v_pk_mul_f32 v[56:57], v[56:57], v[66:67] op_sel_hi:[1,0]
	v_pk_mul_f32 v[58:59], v[58:59], v[66:67] op_sel_hi:[1,0]
	v_pk_mul_f32 v[60:61], v[60:61], v[66:67] op_sel_hi:[1,0]
	v_pk_mul_f32 v[62:63], v[62:63], v[66:67] op_sel_hi:[1,0]
	v_cvt_pk_bf16_f32 v226, v56, v57
	v_cvt_pk_bf16_f32 v227, v58, v59
	v_cvt_pk_bf16_f32 v228, v60, v61
	v_cvt_pk_bf16_f32 v229, v62, v63
	s_nop 1
	v_permlane32_swap_b32_e32 v226, v228
	v_permlane32_swap_b32_e32 v227, v229
	global_store_dwordx4 v[68:69], v[226:229], off offset:32
	v_pk_mul_f32 v[32:33], v[32:33], v[66:67] op_sel_hi:[1,0]
	v_pk_mul_f32 v[34:35], v[34:35], v[66:67] op_sel_hi:[1,0]
	v_pk_mul_f32 v[36:37], v[36:37], v[66:67] op_sel_hi:[1,0]
	v_pk_mul_f32 v[38:39], v[38:39], v[66:67] op_sel_hi:[1,0]
	v_cvt_pk_bf16_f32 v230, v32, v33
	v_cvt_pk_bf16_f32 v231, v34, v35
	v_cvt_pk_bf16_f32 v232, v36, v37
	v_cvt_pk_bf16_f32 v233, v38, v39
	s_nop 1
	v_permlane32_swap_b32_e32 v230, v232
	v_permlane32_swap_b32_e32 v231, v233
	global_store_dwordx4 v[68:69], v[230:233], off offset:64
	v_pk_mul_f32 v[40:41], v[40:41], v[66:67] op_sel_hi:[1,0]
	v_pk_mul_f32 v[42:43], v[42:43], v[66:67] op_sel_hi:[1,0]
	v_pk_mul_f32 v[44:45], v[44:45], v[66:67] op_sel_hi:[1,0]
	v_pk_mul_f32 v[46:47], v[46:47], v[66:67] op_sel_hi:[1,0]
	v_cvt_pk_bf16_f32 v234, v40, v41
	v_cvt_pk_bf16_f32 v235, v42, v43
	v_cvt_pk_bf16_f32 v236, v44, v45
	v_cvt_pk_bf16_f32 v237, v46, v47
	s_nop 1
	v_permlane32_swap_b32_e32 v234, v236
	v_permlane32_swap_b32_e32 v235, v237
	global_store_dwordx4 v[68:69], v[234:237], off offset:96

; __device__ __forceinline__ u16 bf16_1(float a) { return (u16)(pk_bf16(a, 0.f) & 0xffffu); }
; __device__ void run_phase(CP& p, int ph, char* lds) {
;     ...
;         for (int tb = 0; tb < 2; ++tb) {
;           const int tok = tbase + tb * 32 + l32;
;           if (tok < M) {
;             const float rs = rsqrtf(p.ss1[tok] * (1.f / 1024.f) + EPSN);
;             if (!G.meta && nbase >= 2048 && nbase < 3072) {
;               const int s = tok >> G.lgS, t = 16 + (tok & (G.S - 1));
;               const int Lp = (G.L + 63) & ~63;
;               const int pos = (t & ~12) | ((t & 4) << 1) | ((t & 8) >> 1);
;               u16* vt = p.VT + ((size_t)(s * 1024 + (nbase - 2048)) * Lp) + pos;
; #pragma unroll
;               for (int nb = 0; nb < 2; ++nb)
; #pragma unroll
;                 for (int r = 0; r < 16; ++r) {
;                   const int dvl = nb * 32 + 8 * (r >> 2) + 4 * h + (r & 3);
;                   vt[(size_t)dvl * Lp] = bf16_1(acc[nb][tb][r] * rs);
;                 }
;             } else {
;               u16* dst = Pout + (size_t)tok * NIN + nbase + 4 * h;
; #pragma unroll
;               for (int nb = 0; nb < 2; ++nb)
; #pragma unroll
;                 for (int i = 0; i < 4; ++i)
;                   *(u32x2*)(dst + nb * 32 + 8 * i) = (u32x2){pk_bf16(acc[nb][tb][4 * i] * rs, acc[nb][tb][4 * i + 1] * rs),
;                                                              pk_bf16(acc[nb][tb][4 * i + 2] * rs, acc[nb][tb][4 * i + 3] * rs)};
;             }
.LBB0_638:
	s_or_b64 exec, exec, s[34:35]
	v_or_b32_e32 v33, 32, v64
	v_cmp_gt_i32_e64 s[42:43], s62, v33
	s_and_saveexec_b64 s[34:35], s[42:43]
	s_cbranch_execz .LBB0_614
	v_lshl_add_u64 v[34:35], v[64:65], 2, s[48:49]
	s_and_b64 s[0:1], s[86:87], s[40:41]
	s_xor_b64 s[0:1], s[0:1], -1
	v_mov_b32_e32 v32, v245
	v_fmamk_f32 v32, v32, 0x3a800000, v205
	v_cmp_gt_f32_e64 s[42:43], s21, v32
	v_mul_f32_e32 v34, 0x4b800000, v32
	s_nop 0
	v_cndmask_b32_e64 v32, v32, v34, s[42:43]
	v_rsq_f32_e32 v32, v32
	s_nop 0
	v_mul_f32_e32 v34, 0x45800000, v32
	v_cndmask_b32_e64 v32, v32, v34, s[42:43]
	s_and_saveexec_b64 s[6:7], s[0:1]
	s_xor_b64 s[6:7], exec, s[6:7]
	s_cbranch_execz .LBB0_641
	v_mov_b64_e32 v[34:35], s[46:47]
	v_mad_i64_i32 v[34:35], s[0:1], v33, s74, v[34:35]
	v_lshl_add_u64 v[34:35], v[144:145], 1, v[34:35]
	v_lshlrev_b32_e32 v160, 1, v67
	v_lshl_add_u64 v[34:35], v[34:35], 0, v[160:161]
	v_lshl_add_u64 v[34:35], v[34:35], 0, v[160:161]
	v_pk_mul_f32 v[16:17], v[16:17], v[32:33] op_sel_hi:[1,0]
	v_pk_mul_f32 v[18:19], v[18:19], v[32:33] op_sel_hi:[1,0]
	v_pk_mul_f32 v[20:21], v[20:21], v[32:33] op_sel_hi:[1,0]
	v_pk_mul_f32 v[22:23], v[22:23], v[32:33] op_sel_hi:[1,0]
	v_cvt_pk_bf16_f32 v222, v16, v17
	v_cvt_pk_bf16_f32 v223, v18, v19
	v_cvt_pk_bf16_f32 v224, v20, v21
	v_cvt_pk_bf16_f32 v225, v22, v23
	s_nop 1
	v_permlane32_swap_b32_e32 v222, v224
	v_permlane32_swap_b32_e32 v223, v225
	global_store_dwordx4 v[34:35], v[222:225], off
	v_pk_mul_f32 v[24:25], v[24:25], v[32:33] op_sel_hi:[1,0]
	v_pk_mul_f32 v[26:27], v[26:27], v[32:33] op_sel_hi:[1,0]
	v_pk_mul_f32 v[28:29], v[28:29], v[32:33] op_sel_hi:[1,0]
	v_pk_mul_f32 v[30:31], v[30:31], v[32:33] op_sel_hi:[1,0]
	v_cvt_pk_bf16_f32 v226, v24, v25
	v_cvt_pk_bf16_f32 v227, v26, v27
	v_cvt_pk_bf16_f32 v228, v28, v29
	v_cvt_pk_bf16_f32 v229, v30, v31
	s_nop 1
	v_permlane32_swap_b32_e32 v226, v228
	v_permlane32_swap_b32_e32 v227, v229
	global_store_dwordx4 v[34:35], v[226:229], off offset:32
	v_pk_mul_f32 v[0:1], v[0:1], v[32:33] op_sel_hi:[1,0]
	v_pk_mul_f32 v[2:3], v[2:3], v[32:33] op_sel_hi:[1,0]
	v_pk_mul_f32 v[4:5], v[4:5], v[32:33] op_sel_hi:[1,0]
	v_pk_mul_f32 v[6:7], v[6:7], v[32:33] op_sel_hi:[1,0]
	v_cvt_pk_bf16_f32 v230, v0, v1
	v_cvt_pk_bf16_f32 v231, v2, v3
	v_cvt_pk_bf16_f32 v232, v4, v5
	v_cvt_pk_bf16_f32 v233, v6, v7
	s_nop 1
	v_permlane32_swap_b32_e32 v230, v232
	v_permlane32_swap_b32_e32 v231, v233
	global_store_dwordx4 v[34:35], v[230:233], off offset:64
	v_pk_mul_f32 v[8:9], v[8:9], v[32:33] op_sel_hi:[1,0]
	v_pk_mul_f32 v[10:11], v[10:11], v[32:33] op_sel_hi:[1,0]
	v_pk_mul_f32 v[12:13], v[12:13], v[32:33] op_sel_hi:[1,0]
	v_pk_mul_f32 v[14:15], v[14:15], v[32:33] op_sel_hi:[1,0]
	v_cvt_pk_bf16_f32 v234, v8, v9
	v_cvt_pk_bf16_f32 v235, v10, v11
	v_cvt_pk_bf16_f32 v236, v12, v13
	v_cvt_pk_bf16_f32 v237, v14, v15
	s_nop 1
	v_permlane32_swap_b32_e32 v234, v236
	v_permlane32_swap_b32_e32 v235, v237
	global_store_dwordx4 v[34:35], v[234:237], off offset:96
